# v81 + mLSTM scan: S1 k-loop issues all ten LDS fragment reads at the top of each iteration; seg-E reads batched; shift/broadcast via wave_shr DPP and v_readlane
# speedup vs baseline: 1.0098x; 1.0012x over previous
.LBB0_204:
	s_or_b64 exec, exec, s[86:87]
	s_andn2_b64 vcc, exec, s[82:83]
	s_waitcnt lgkmcnt(0)
	s_barrier
	s_cbranch_vccnz .LBB0_208
	ds_read_b64 v[72:73], v159
	ds_read_b64 v[76:77], v160
	s_waitcnt lgkmcnt(1)
	v_add_f32_e32 v73, v72, v73
	v_mov_b32_e32 v75, v73
	s_nop 1
	v_add_f32_dpp v75, v75, v75 row_shr:1 row_mask:0xf bank_mask:0xf
	s_nop 1
	v_add_f32_dpp v75, v75, v75 row_shr:2 row_mask:0xf bank_mask:0xf
	s_nop 1
	v_add_f32_dpp v75, v75, v75 row_shr:4 row_mask:0xf bank_mask:0xf
	s_nop 1
	v_add_f32_dpp v75, v75, v75 row_shr:8 row_mask:0xf bank_mask:0xf
	s_nop 1
	v_add_f32_dpp v75, v75, v75 row_bcast:15 row_mask:0xa bank_mask:0xf
	s_nop 1
	v_add_f32_dpp v75, v75, v75 row_bcast:31 row_mask:0xc bank_mask:0xf
	s_waitcnt lgkmcnt(0)
	v_sub_f32_e32 v73, v75, v73
	v_add_f32_e32 v74, v72, v73
	v_pk_add_f32 v[76:77], v[76:77], v[74:75] neg_lo:[0,1] neg_hi:[0,1]
	ds_bpermute_b32 v72, v162, v75
	v_max_f32_e32 v73, v76, v77
	s_nop 1
	v_max_f32_dpp v73, v73, v73 row_shr:1 row_mask:0xf bank_mask:0xf
	s_nop 1
	v_max_f32_dpp v73, v73, v73 row_shr:2 row_mask:0xf bank_mask:0xf
	s_nop 1
	v_max_f32_dpp v73, v73, v73 row_shr:4 row_mask:0xf bank_mask:0xf
	s_nop 1
	v_max_f32_dpp v73, v73, v73 row_shr:8 row_mask:0xf bank_mask:0xf
	s_nop 1
	v_max_f32_dpp v73, v73, v73 row_bcast:15 row_mask:0xa bank_mask:0xf
	s_nop 1
	v_max_f32_dpp v73, v73, v73 row_bcast:31 row_mask:0xc bank_mask:0xf
	s_nop 1
	v_mov_b32_dpp v78, v73 wave_shr:1 row_mask:0xf bank_mask:0xf
	v_max_f32_e32 v73, v73, v73
	v_max_f32_e32 v79, v135, v135
	v_max_f32_e32 v79, v79, v73
	v_add_f32_e32 v75, v75, v79
	s_waitcnt lgkmcnt(0)
	v_cndmask_b32_e64 v78, v78, v218, s[4:5]
	v_max3_f32 v78, v135, v78, v76
	v_add_f32_e32 v74, v74, v78
	v_readlane_b32 s98, v79, 63
	v_mul_f32_e32 v74, 0xbfb8aa3b, v74
	v_mul_f32_e32 v75, 0xbfb8aa3b, v75
	v_exp_f32_e32 v74, v74
	v_exp_f32_e32 v75, v75
	ds_write_b64 v163, v[76:77]
	ds_write_b64 v164, v[78:79]
	v_sub_f32_e32 v80, v135, v78
	v_sub_f32_e32 v81, v135, v79
	ds_write_b64 v166, v[74:75]
	v_mov_b32_e32 v73, s98
	v_sub_f32_e32 v74, v76, v73
	v_sub_f32_e32 v75, v77, v73
	v_mul_f32_e32 v80, 0x3fb8aa3b, v80
	v_mul_f32_e32 v81, 0x3fb8aa3b, v81
	v_mul_f32_e32 v74, 0x3fb8aa3b, v74
	v_mul_f32_e32 v75, 0x3fb8aa3b, v75
	v_exp_f32_e32 v80, v80
	v_exp_f32_e32 v81, v81
	v_exp_f32_e32 v74, v74
	v_exp_f32_e32 v75, v75
	ds_write_b64 v165, v[80:81]
	ds_write_b64 v167, v[74:75]
	s_and_saveexec_b64 s[86:87], s[4:5]
	s_cbranch_execz .LBB0_207
	v_sub_f32_e32 v74, v135, v73
	v_mul_f32_e32 v74, 0x3fb8aa3b, v74
	v_exp_f32_e32 v74, v74
	v_mov_b32_e32 v75, s33
	ds_write_b32 v75, v74

.Lpf_skip:
.LBB0_209:
	v_add_u32_e32 v202, s85, v214
	v_add_u32_e32 v219, s85, v213
	v_add_u32_e32 v236, s85, v212
	ds_read_b128 v[120:123], v202 offset:34816
	ds_read_b128 v[124:127], v219
	ds_read_b128 v[220:223], v219 offset:4352
	ds_read_b128 v[224:227], v219 offset:8704
	ds_read_b128 v[228:231], v219 offset:13056
	ds_read_b128 v[232:235], v202
	v_add_u32_e32 v245, 0x1dc00, v236
	v_add_u32_e32 v236, 0x1ed00, v236
	ds_read_b128 v[246:249], v245
	ds_read_b128 v[236:239], v236
	ds_read_b128 v[250:253], v202 offset:39168
	s_add_i32 s85, s85, 64
	s_cmpk_eq_i32 s85, 0x100
	s_waitcnt lgkmcnt(7)
	v_mfma_f32_16x16x32_bf16 v[116:119], v[120:123], v[124:127], v[116:119]
	s_waitcnt lgkmcnt(6)
	v_mfma_f32_16x16x32_bf16 v[112:115], v[120:123], v[220:223], v[112:115]
	s_waitcnt lgkmcnt(5)
	v_mfma_f32_16x16x32_bf16 v[104:107], v[120:123], v[224:227], v[104:107]
	s_waitcnt lgkmcnt(4)
	v_mfma_f32_16x16x32_bf16 v[96:99], v[120:123], v[228:231], v[96:99]
	ds_read_b128 v[120:123], v202 offset:4352
	s_waitcnt lgkmcnt(3)
	v_mfma_f32_16x16x32_bf16 v[84:87], v[232:235], v[246:249], v[84:87]
	s_waitcnt lgkmcnt(2)
	v_mfma_f32_16x16x32_bf16 v[80:83], v[232:235], v[236:239], v[80:83]
	s_waitcnt lgkmcnt(1)
	v_mfma_f32_16x16x32_bf16 v[108:111], v[250:253], v[124:127], v[108:111]
	v_mfma_f32_16x16x32_bf16 v[100:103], v[250:253], v[220:223], v[100:103]
	v_mfma_f32_16x16x32_bf16 v[92:95], v[250:253], v[224:227], v[92:95]
	v_mfma_f32_16x16x32_bf16 v[88:91], v[250:253], v[228:231], v[88:91]
	s_waitcnt lgkmcnt(0)
	v_mfma_f32_16x16x32_bf16 v[76:79], v[120:123], v[246:249], v[76:79]
	v_mfma_f32_16x16x32_bf16 v[72:75], v[120:123], v[236:239], v[72:75]
	s_cbranch_scc0 .LBB0_209
	ds_read_b128 v[120:123], v169
	ds_read_b128 v[124:127], v169 offset:16
	ds_read_b128 v[220:223], v169 offset:32
	ds_read_b128 v[224:227], v169 offset:48
	ds_read_b128 v[228:231], v170
	ds_read_b128 v[232:235], v170 offset:16
	ds_read_b128 v[236:239], v170 offset:32
	ds_read_b128 v[240:243], v170 offset:48
	s_waitcnt lgkmcnt(7)
	v_lshlrev_b32_e32 v202, 16, v120
	v_and_b32_e32 v120, 0xffff0000, v120
	s_waitcnt lgkmcnt(3)
	v_mul_f32_e32 v120, v229, v120
	v_fmac_f32_e32 v120, v228, v202
	v_lshlrev_b32_e32 v202, 16, v121
	v_fmac_f32_e32 v120, v230, v202
	v_and_b32_e32 v121, 0xffff0000, v121
	v_fmac_f32_e32 v120, v231, v121
	v_lshlrev_b32_e32 v121, 16, v122
	s_waitcnt lgkmcnt(2)
	v_fmac_f32_e32 v120, v232, v121
	v_and_b32_e32 v121, 0xffff0000, v122
	v_fmac_f32_e32 v120, v233, v121
	v_lshlrev_b32_e32 v121, 16, v123
	v_fmac_f32_e32 v120, v234, v121
	v_and_b32_e32 v121, 0xffff0000, v123
	v_fmac_f32_e32 v120, v235, v121
	v_and_b32_e32 v121, 0xffff0000, v124
	v_add_f32_e32 v202, 0, v120
	v_lshlrev_b32_e32 v120, 16, v124
	s_waitcnt lgkmcnt(1)
	v_mul_f32_e32 v124, v237, v121
	v_fmac_f32_e32 v124, v236, v120
	v_lshlrev_b32_e32 v120, 16, v125
	v_fmac_f32_e32 v124, v238, v120
	v_and_b32_e32 v120, 0xffff0000, v125
	v_fmac_f32_e32 v124, v239, v120
	v_lshlrev_b32_e32 v120, 16, v126
	s_waitcnt lgkmcnt(0)
	v_fmac_f32_e32 v124, v240, v120
	v_and_b32_e32 v120, 0xffff0000, v126
	v_fmac_f32_e32 v124, v241, v120
	v_lshlrev_b32_e32 v120, 16, v127
	v_fmac_f32_e32 v124, v242, v120
	v_and_b32_e32 v120, 0xffff0000, v127
	v_fmac_f32_e32 v124, v243, v120
	ds_read_b128 v[120:123], v170 offset:64
	v_add_f32_e32 v202, v202, v124
	ds_read_b128 v[124:127], v170 offset:80
	v_lshlrev_b32_e32 v219, 16, v220
	v_and_b32_e32 v220, 0xffff0000, v220
	s_waitcnt lgkmcnt(1)
	v_mul_f32_e32 v220, v121, v220
	v_fmac_f32_e32 v220, v120, v219
	v_lshlrev_b32_e32 v120, 16, v221
	v_fmac_f32_e32 v220, v122, v120
	v_and_b32_e32 v120, 0xffff0000, v221
	v_fmac_f32_e32 v220, v123, v120
	v_lshlrev_b32_e32 v120, 16, v222
	s_waitcnt lgkmcnt(0)
	v_fmac_f32_e32 v220, v124, v120
	v_and_b32_e32 v120, 0xffff0000, v222
	v_fmac_f32_e32 v220, v125, v120
	v_lshlrev_b32_e32 v120, 16, v223
	v_fmac_f32_e32 v220, v126, v120
	v_and_b32_e32 v120, 0xffff0000, v223
	v_fmac_f32_e32 v220, v127, v120
	ds_read_b128 v[120:123], v170 offset:96
	ds_read_b128 v[124:127], v170 offset:112
	v_add_f32_e32 v202, v202, v220
	v_and_b32_e32 v220, 0xffff0000, v224
	v_lshlrev_b32_e32 v219, 16, v224
	s_waitcnt lgkmcnt(1)
	v_mul_f32_e32 v121, v121, v220
	v_fmac_f32_e32 v121, v120, v219
	v_lshlrev_b32_e32 v120, 16, v225
	v_fmac_f32_e32 v121, v122, v120
	v_and_b32_e32 v120, 0xffff0000, v225
	v_fmac_f32_e32 v121, v123, v120
	v_lshlrev_b32_e32 v120, 16, v226
	s_waitcnt lgkmcnt(0)
	v_fmac_f32_e32 v121, v124, v120
	v_and_b32_e32 v120, 0xffff0000, v226
	v_fmac_f32_e32 v121, v125, v120
	v_lshlrev_b32_e32 v120, 16, v227
	v_fmac_f32_e32 v121, v126, v120
	v_and_b32_e32 v120, 0xffff0000, v227
	v_fmac_f32_e32 v121, v127, v120
	v_add_f32_e32 v120, v202, v121
	s_nop 1
	v_add_f32_dpp v120, v120, v120 quad_perm:[1,0,3,2] row_mask:0xf bank_mask:0xf
	s_waitcnt lgkmcnt(0)
	s_nop 1
	v_add_f32_dpp v120, v120, v120 quad_perm:[2,3,0,1] row_mask:0xf bank_mask:0xf
	s_and_saveexec_b64 s[86:87], s[6:7]
	s_cbranch_execz .LBB0_212
	s_waitcnt lgkmcnt(0)
	s_nop 0
	ds_write_b32 v173, v120

.LBB0_226:
	s_or_b64 exec, exec, s[86:87]
	v_add_u32_e32 v92, s97, v174
	s_waitcnt lgkmcnt(0)
	s_barrier
	ds_read_b128 v[246:249], v92
	ds_read_b128 v[250:253], v92 offset:64
	v_mov_b32_e32 v88, s33
	ds_read_b32 v88, v88
	s_mov_b32 s86, 0
	s_waitcnt lgkmcnt(2)
	v_pk_mul_f32 v[86:87], v[86:87], v[248:249]
	v_pk_mul_f32 v[84:85], v[84:85], v[246:247]
	v_pk_mul_f32 v[82:83], v[82:83], v[248:249]
	v_pk_mul_f32 v[80:81], v[80:81], v[246:247]
	s_nop 0
	s_waitcnt lgkmcnt(1)
	v_pk_mul_f32 v[76:77], v[76:77], v[250:251]
	v_pk_mul_f32 v[72:73], v[72:73], v[250:251]
	s_nop 0
	s_nop 0
	v_pk_mul_f32 v[78:79], v[78:79], v[252:253]
	v_pk_mul_f32 v[74:75], v[74:75], v[252:253]
	s_waitcnt lgkmcnt(0)
	v_pk_mul_f32 v[58:59], v[58:59], v[88:89] op_sel_hi:[1,0]
	v_pk_mul_f32 v[56:57], v[56:57], v[88:89] op_sel_hi:[1,0]
	v_pk_mul_f32 v[62:63], v[62:63], v[88:89] op_sel_hi:[1,0]
	v_pk_mul_f32 v[60:61], v[60:61], v[88:89] op_sel_hi:[1,0]
	v_pk_mul_f32 v[66:67], v[66:67], v[88:89] op_sel_hi:[1,0]
	v_pk_mul_f32 v[64:65], v[64:65], v[88:89] op_sel_hi:[1,0]
	v_pk_mul_f32 v[70:71], v[70:71], v[88:89] op_sel_hi:[1,0]
	v_pk_mul_f32 v[68:69], v[68:69], v[88:89] op_sel_hi:[1,0]
